# prep step 4a rewritten by hand: f32 MFMA (16x16x4) off-diagonal updates + columnwise in-block substitution on wave 0; T to split-bf16 fragments by all 8 waves
# speedup vs baseline: 1.0954x; 1.0294x over previous
; __device__ void prep_unit(unsigned char* lds, int bh, int n, const bf16_t* pc, const float* scal, const float* convw  , float alog, float dtb, unsigned char* unit, float* egl, unsigned* flag, unsigned fval) {
;     ...
;     if (wid == 0) {
;         const int c = lane;
;         int zv = 0; asm volatile("" : "+v"(zv)); const float* AmV = Am + zv;
;         for (int rb = 0; rb < 4; ++rb) {
;             typedef float f32x2v __attribute__((ext_vector_type(2)));
;             f32x2v sp[8];
; #pragma unroll
;             for (int q = 0; q < 8; ++q) { sp[q][0] = (16 * rb + 2 * q == c) ? 1.0f : 0.0f; sp[q][1] = (16 * rb + 2 * q + 1 == c) ? 1.0f : 0.0f; }
;             for (int j4 = 0; j4 < 4 * rb; ++j4) {
;                 const float t0 = Am[(4 * j4 + 0) * 68 + c], t1 = Am[(4 * j4 + 1) * 68 + c], t2 = Am[(4 * j4 + 2) * 68 + c], t3 = Am[(4 * j4 + 3) * 68 + c];
;                 const f32x2v T0 = {t0, t0}, T1 = {t1, t1}, T2 = {t2, t2}, T3 = {t3, t3};
; #pragma unroll
;                 for (int q = 0; q < 8; ++q) { const f32x4 a4 = *(const f32x4*)(AmV + (16 * rb + 2 * q) * 68 + 4 * j4), b4 = *(const f32x4*)(AmV + (16 * rb + 2 * q + 1) * 68 + 4 * j4);
;                     f32x2v acc2 = sp[q];
;                     acc2 -= (f32x2v){a4[0], b4[0]} * T0; acc2 -= (f32x2v){a4[1], b4[1]} * T1; acc2 -= (f32x2v){a4[2], b4[2]} * T2; acc2 -= (f32x2v){a4[3], b4[3]} * T3;
;                     sp[q] = acc2; }
;             }
;             float sx[16];
; #pragma unroll
;             for (int r = 0; r < 16; ++r) sx[r] = sp[r >> 1][r & 1];
; #pragma unroll
;             for (int r = 1; r < 16; ++r) {
; #pragma unroll
;                 for (int q4 = 0; q4 < (r + 3) / 4; ++q4) { const f32x4 a4 = *(const f32x4*)(AmV + (16 * rb + r) * 68 + 16 * rb + 4 * q4);
; #pragma unroll
;                     for (int jj = 0; jj < 4; ++jj) if (4 * q4 + jj < r) sx[r] -= a4[jj] * sx[4 * q4 + jj]; }
;             }
.LBB0_405:
	s_andn2_saveexec_b64 s[0:1], s[2:3]
	s_cbranch_execz .LBB0_414
	v_lshlrev_b32_e32 v240, 2, v157
	v_add_u32_e32 v240, 0x19800, v240
	v_and_b32_e32 v244, 15, v157
	v_lshrrev_b32_e32 v245, 4, v157
	v_mul_u32_u24_e32 v246, 0x110, v244
	v_lshl_add_u32 v246, v245, 4, v246
	v_add_u32_e32 v246, 0x19800, v246
	v_mul_u32_u24_e32 v247, 0x440, v245
	v_lshl_add_u32 v247, v244, 2, v247
	v_add_u32_e32 v248, 0x22400, v247
	v_lshlrev_b32_e32 v249, 10, v245
	v_lshl_add_u32 v249, v244, 2, v249
	v_add_u32_e32 v249, 0x22400, v249
	v_add_u32_e32 v247, 0x19800, v247
	v_lshlrev_b32_e32 v250, 2, v157
	v_add_u32_e32 v250, 0x22400, v250
	v_lshlrev_b32_e32 v251, 2, v245
	v_sub_u32_e32 v251, v244, v251
	v_subrev_u32_e32 v242, 0, v157
	v_cmp_eq_u32_e64 s[2:3], 0, v242
	v_cmp_eq_u32_e64 s[4:5], 1, v242
	v_cmp_eq_u32_e64 s[8:9], 2, v242
	v_cmp_eq_u32_e64 s[10:11], 3, v242
	v_cmp_eq_u32_e64 s[14:15], 4, v242
	v_cmp_eq_u32_e64 s[16:17], 5, v242
	v_cmp_eq_u32_e64 s[18:19], 6, v242
	v_cmp_eq_u32_e64 vcc, 7, v242
	v_cndmask_b32_e64 v2, 0, 1.0, s[2:3]
	v_cndmask_b32_e64 v3, 0, 1.0, s[4:5]
	v_cndmask_b32_e64 v4, 0, 1.0, s[8:9]
	v_cndmask_b32_e64 v5, 0, 1.0, s[10:11]
	v_cndmask_b32_e64 v6, 0, 1.0, s[14:15]
	v_cndmask_b32_e64 v7, 0, 1.0, s[16:17]
	v_cndmask_b32_e64 v8, 0, 1.0, s[18:19]
	v_cndmask_b32_e64 v9, 0, 1.0, vcc
	v_cmp_eq_u32_e64 s[2:3], 8, v242
	v_cmp_eq_u32_e64 s[4:5], 9, v242
	v_cmp_eq_u32_e64 s[8:9], 10, v242
	v_cmp_eq_u32_e64 s[10:11], 11, v242
	v_cmp_eq_u32_e64 s[14:15], 12, v242
	v_cmp_eq_u32_e64 s[16:17], 13, v242
	v_cmp_eq_u32_e64 s[18:19], 14, v242
	v_cmp_eq_u32_e64 vcc, 15, v242
	v_cndmask_b32_e64 v10, 0, 1.0, s[2:3]
	v_cndmask_b32_e64 v11, 0, 1.0, s[4:5]
	v_cndmask_b32_e64 v12, 0, 1.0, s[8:9]
	v_cndmask_b32_e64 v13, 0, 1.0, s[10:11]
	v_cndmask_b32_e64 v14, 0, 1.0, s[14:15]
	v_cndmask_b32_e64 v15, 0, 1.0, s[16:17]
	v_cndmask_b32_e64 v16, 0, 1.0, s[18:19]
	v_cndmask_b32_e64 v17, 0, 1.0, vcc
	v_mov_b32_e32 v241, 0x19800
	ds_read_b128 v[22:25], v241 offset:272
	ds_read_b128 v[26:29], v241 offset:544
	ds_read_b128 v[30:33], v241 offset:816
	ds_read_b128 v[34:37], v241 offset:1088
	ds_read_b128 v[38:41], v241 offset:1360
	ds_read_b128 v[42:45], v241 offset:1632
	ds_read_b128 v[46:49], v241 offset:1904
	ds_read_b128 v[50:53], v241 offset:2176
	ds_read_b128 v[54:57], v241 offset:2448
	ds_read_b128 v[58:61], v241 offset:2720
	ds_read_b128 v[62:65], v241 offset:2992
	ds_read_b128 v[66:69], v241 offset:3264
	ds_read_b128 v[70:73], v241 offset:3536
	ds_read_b128 v[74:77], v241 offset:3808
	ds_read_b128 v[78:81], v241 offset:4080
	s_waitcnt lgkmcnt(0)
	ds_read_b128 v[82:85], v241 offset:1376
	ds_read_b128 v[86:89], v241 offset:1648
	ds_read_b128 v[90:93], v241 offset:1920
	ds_read_b128 v[96:99], v241 offset:2192
	ds_read_b128 v[100:103], v241 offset:2464
	ds_read_b128 v[110:113], v241 offset:2736
	ds_read_b128 v[114:117], v241 offset:3008
	ds_read_b128 v[118:121], v241 offset:3280
	ds_read_b128 v[122:125], v241 offset:3552
	ds_read_b128 v[126:129], v241 offset:3824
	ds_read_b128 v[130:133], v241 offset:4096
	v_fma_f32 v3, -v22, v2, v3
	v_fma_f32 v4, -v26, v2, v4
	v_fma_f32 v5, -v30, v2, v5
	v_fma_f32 v6, -v34, v2, v6
	v_fma_f32 v7, -v38, v2, v7
	v_fma_f32 v8, -v42, v2, v8
	v_fma_f32 v9, -v46, v2, v9
	v_fma_f32 v10, -v50, v2, v10
	v_fma_f32 v11, -v54, v2, v11
	v_fma_f32 v12, -v58, v2, v12
	v_fma_f32 v13, -v62, v2, v13
	v_fma_f32 v14, -v66, v2, v14
	v_fma_f32 v15, -v70, v2, v15
	v_fma_f32 v16, -v74, v2, v16
	v_fma_f32 v17, -v78, v2, v17
	v_fma_f32 v4, -v27, v3, v4
	v_fma_f32 v5, -v31, v3, v5
	v_fma_f32 v6, -v35, v3, v6
	v_fma_f32 v7, -v39, v3, v7
	v_fma_f32 v8, -v43, v3, v8
	v_fma_f32 v9, -v47, v3, v9
	v_fma_f32 v10, -v51, v3, v10
	v_fma_f32 v11, -v55, v3, v11
	v_fma_f32 v12, -v59, v3, v12
	v_fma_f32 v13, -v63, v3, v13
	v_fma_f32 v14, -v67, v3, v14
	v_fma_f32 v15, -v71, v3, v15
	v_fma_f32 v16, -v75, v3, v16
	v_fma_f32 v17, -v79, v3, v17
	v_fma_f32 v5, -v32, v4, v5
	v_fma_f32 v6, -v36, v4, v6
	v_fma_f32 v7, -v40, v4, v7
	v_fma_f32 v8, -v44, v4, v8
	v_fma_f32 v9, -v48, v4, v9
	v_fma_f32 v10, -v52, v4, v10
	v_fma_f32 v11, -v56, v4, v11
	v_fma_f32 v12, -v60, v4, v12
	v_fma_f32 v13, -v64, v4, v13
	v_fma_f32 v14, -v68, v4, v14
	v_fma_f32 v15, -v72, v4, v15
	v_fma_f32 v16, -v76, v4, v16
	v_fma_f32 v17, -v80, v4, v17
	v_fma_f32 v6, -v37, v5, v6
	v_fma_f32 v7, -v41, v5, v7
	v_fma_f32 v8, -v45, v5, v8
	v_fma_f32 v9, -v49, v5, v9
	v_fma_f32 v10, -v53, v5, v10
	v_fma_f32 v11, -v57, v5, v11
	v_fma_f32 v12, -v61, v5, v12
	v_fma_f32 v13, -v65, v5, v13
	v_fma_f32 v14, -v69, v5, v14
	v_fma_f32 v15, -v73, v5, v15
	v_fma_f32 v16, -v77, v5, v16
	v_fma_f32 v17, -v81, v5, v17
	s_waitcnt lgkmcnt(0)
	ds_read_b128 v[134:137], v241 offset:2480
	ds_read_b128 v[138:141], v241 offset:2752
	ds_read_b128 v[142:145], v241 offset:3024
	ds_read_b128 v[146:149], v241 offset:3296
	ds_read_b128 v[150:153], v241 offset:3568
	ds_read_b128 v[158:161], v241 offset:3840
	ds_read_b128 v[162:165], v241 offset:4112
	v_fma_f32 v7, -v82, v6, v7
	v_fma_f32 v8, -v86, v6, v8
	v_fma_f32 v9, -v90, v6, v9
	v_fma_f32 v10, -v96, v6, v10
	v_fma_f32 v11, -v100, v6, v11
	v_fma_f32 v12, -v110, v6, v12
	v_fma_f32 v13, -v114, v6, v13
	v_fma_f32 v14, -v118, v6, v14
	v_fma_f32 v15, -v122, v6, v15
	v_fma_f32 v16, -v126, v6, v16
	v_fma_f32 v17, -v130, v6, v17
	v_fma_f32 v8, -v87, v7, v8
	v_fma_f32 v9, -v91, v7, v9
	v_fma_f32 v10, -v97, v7, v10
	v_fma_f32 v11, -v101, v7, v11
	v_fma_f32 v12, -v111, v7, v12
	v_fma_f32 v13, -v115, v7, v13
	v_fma_f32 v14, -v119, v7, v14
	v_fma_f32 v15, -v123, v7, v15
	v_fma_f32 v16, -v127, v7, v16
	v_fma_f32 v17, -v131, v7, v17
	v_fma_f32 v9, -v92, v8, v9
	v_fma_f32 v10, -v98, v8, v10
	v_fma_f32 v11, -v102, v8, v11
	v_fma_f32 v12, -v112, v8, v12
	v_fma_f32 v13, -v116, v8, v13
	v_fma_f32 v14, -v120, v8, v14
	v_fma_f32 v15, -v124, v8, v15
	v_fma_f32 v16, -v128, v8, v16
	v_fma_f32 v17, -v132, v8, v17
	v_fma_f32 v10, -v99, v9, v10
	v_fma_f32 v11, -v103, v9, v11
	v_fma_f32 v12, -v113, v9, v12
	v_fma_f32 v13, -v117, v9, v13
	v_fma_f32 v14, -v121, v9, v14
	v_fma_f32 v15, -v125, v9, v15
	v_fma_f32 v16, -v129, v9, v16
	v_fma_f32 v17, -v133, v9, v17
	s_waitcnt lgkmcnt(0)
; __device__ __forceinline__ unsigned pack2(float lo, float hi) { return pg8::cvt_pk_bf16(lo, hi); }
; __device__ void prep_unit(unsigned char* lds, int bh, int n, const bf16_t* pc, const float* scal, const float* convw  , float alog, float dtb, unsigned char* unit, float* egl, unsigned* flag, unsigned fval) {
;     ...
;             for (int j4 = 0; j4 < 4 * rb; ++j4) {
;                 const float t0 = Am[(4 * j4 + 0) * 68 + c], t1 = Am[(4 * j4 + 1) * 68 + c], t2 = Am[(4 * j4 + 2) * 68 + c], t3 = Am[(4 * j4 + 3) * 68 + c];
;                 const f32x2v T0 = {t0, t0}, T1 = {t1, t1}, T2 = {t2, t2}, T3 = {t3, t3};
; #pragma unroll
;                 for (int q = 0; q < 8; ++q) { const f32x4 a4 = *(const f32x4*)(AmV + (16 * rb + 2 * q) * 68 + 4 * j4), b4 = *(const f32x4*)(AmV + (16 * rb + 2 * q + 1) * 68 + 4 * j4);
;                     f32x2v acc2 = sp[q];
;                     acc2 -= (f32x2v){a4[0], b4[0]} * T0; acc2 -= (f32x2v){a4[1], b4[1]} * T1; acc2 -= (f32x2v){a4[2], b4[2]} * T2; acc2 -= (f32x2v){a4[3], b4[3]} * T3;
;                     sp[q] = acc2; }
;             }
;             float sx[16];
; #pragma unroll
;             for (int r = 0; r < 16; ++r) sx[r] = sp[r >> 1][r & 1];
; #pragma unroll
;             for (int r = 1; r < 16; ++r) {
; #pragma unroll
;                 for (int q4 = 0; q4 < (r + 3) / 4; ++q4) { const f32x4 a4 = *(const f32x4*)(AmV + (16 * rb + r) * 68 + 16 * rb + 4 * q4);
; #pragma unroll
;                     for (int jj = 0; jj < 4; ++jj) if (4 * q4 + jj < r) sx[r] -= a4[jj] * sx[4 * q4 + jj]; }
;             }
;             bf16_t* sf = stage + (rb * 2 + (c >> 5)) * 512 + ((c >> 3) & 3) * 128 + (c & 7);
; #pragma unroll
;             for (int r = 0; r < 16; r += 2) {
;                 Am[(16 * rb + r) * 68 + c] = sx[r]; Am[(16 * rb + r + 1) * 68 + c] = sx[r + 1];
;                 const unsigned ph = pack2(sx[r], sx[r + 1]);
;                 const unsigned pl = pack2(sx[r] - __uint_as_float(ph << 16), sx[r + 1] - __uint_as_float(ph & 0xffff0000u));
;                 sf[r * 8] = (bf16_t)(ph & 0xffffu); sf[(r + 1) * 8] = (bf16_t)(ph >> 16);
;                 sf[4096 + r * 8] = (bf16_t)(pl & 0xffffu); sf[4096 + (r + 1) * 8] = (bf16_t)(pl >> 16);
;             }
	ds_read_b128 v[166:169], v241 offset:3584
	ds_read_b128 v[182:185], v241 offset:3856
	ds_read_b128 v[186:189], v241 offset:4128
	v_fma_f32 v11, -v134, v10, v11
	v_fma_f32 v12, -v138, v10, v12
	v_fma_f32 v13, -v142, v10, v13
	v_fma_f32 v14, -v146, v10, v14
	v_fma_f32 v15, -v150, v10, v15
	v_fma_f32 v16, -v158, v10, v16
	v_fma_f32 v17, -v162, v10, v17
	v_fma_f32 v12, -v139, v11, v12
	v_fma_f32 v13, -v143, v11, v13
	v_fma_f32 v14, -v147, v11, v14
	v_fma_f32 v15, -v151, v11, v15
	v_fma_f32 v16, -v159, v11, v16
	v_fma_f32 v17, -v163, v11, v17
	v_fma_f32 v13, -v144, v12, v13
	v_fma_f32 v14, -v148, v12, v14
	v_fma_f32 v15, -v152, v12, v15
	v_fma_f32 v16, -v160, v12, v16
	v_fma_f32 v17, -v164, v12, v17
	v_fma_f32 v14, -v149, v13, v14
	v_fma_f32 v15, -v153, v13, v15
	v_fma_f32 v16, -v161, v13, v16
	v_fma_f32 v17, -v165, v13, v17
	s_waitcnt lgkmcnt(0)
	v_fma_f32 v15, -v166, v14, v15
	v_fma_f32 v16, -v182, v14, v16
	v_fma_f32 v17, -v186, v14, v17
	v_fma_f32 v16, -v183, v15, v16
	v_fma_f32 v17, -v187, v15, v17
	v_fma_f32 v17, -v188, v16, v17
	ds_write_b32 v240, v2 offset:0
	ds_write_b32 v240, v3 offset:272
	ds_write_b32 v240, v4 offset:544
	ds_write_b32 v240, v5 offset:816
	ds_write_b32 v240, v6 offset:1088
	ds_write_b32 v240, v7 offset:1360
	ds_write_b32 v240, v8 offset:1632
	ds_write_b32 v240, v9 offset:1904
	ds_write_b32 v240, v10 offset:2176
	ds_write_b32 v240, v11 offset:2448
	ds_write_b32 v240, v12 offset:2720
	ds_write_b32 v240, v13 offset:2992
	ds_write_b32 v240, v14 offset:3264
	ds_write_b32 v240, v15 offset:3536
	ds_write_b32 v240, v16 offset:3808
	ds_write_b32 v240, v17 offset:4080
	v_mov_b32_e32 v110, 0
	v_mov_b32_e32 v111, 0
	v_mov_b32_e32 v112, 0
	v_mov_b32_e32 v113, 0
	v_cmp_eq_u32_e64 s[2:3], 0, v251
	v_cmp_eq_u32_e64 s[4:5], 1, v251
	v_cmp_eq_u32_e64 s[8:9], 2, v251
	v_cmp_eq_u32_e64 s[10:11], 3, v251
	v_mov_b32_e32 v118, 0
	v_mov_b32_e32 v119, 0
	v_mov_b32_e32 v120, 0
	v_mov_b32_e32 v121, 0
	v_mov_b32_e32 v122, 0
	v_mov_b32_e32 v123, 0
	v_mov_b32_e32 v124, 0
	v_mov_b32_e32 v125, 0
	v_cndmask_b32_e64 v114, 0, 1.0, s[2:3]
	v_cndmask_b32_e64 v115, 0, 1.0, s[4:5]
	v_cndmask_b32_e64 v116, 0, 1.0, s[8:9]
	v_cndmask_b32_e64 v117, 0, 1.0, s[10:11]
	ds_read_b128 v[126:129], v246 offset:4352
	ds_read_b32 v130, v247 offset:0
	ds_read_b32 v131, v247 offset:272
	ds_read_b32 v132, v247 offset:544
	ds_read_b32 v133, v247 offset:816
	s_waitcnt lgkmcnt(4)
	v_xor_b32_e32 v126, 0x80000000, v126
	v_xor_b32_e32 v127, 0x80000000, v127
	v_xor_b32_e32 v128, 0x80000000, v128
	v_xor_b32_e32 v129, 0x80000000, v129
	s_waitcnt lgkmcnt(0)
	s_nop 1
	v_mfma_f32_16x16x4_f32 v[110:113], v126, v130, v[110:113]
	v_mfma_f32_16x16x4_f32 v[110:113], v127, v131, v[110:113]
	v_mfma_f32_16x16x4_f32 v[110:113], v128, v132, v[110:113]
	v_mfma_f32_16x16x4_f32 v[110:113], v129, v133, v[110:113]
	s_nop 7
	s_nop 3
	ds_write_b32 v249, v110 offset:0
	ds_write_b32 v249, v111 offset:256
	ds_write_b32 v249, v112 offset:512
	ds_write_b32 v249, v113 offset:768
	ds_write_b32 v249, v114 offset:64
	ds_write_b32 v249, v115 offset:320
	ds_write_b32 v249, v116 offset:576
	ds_write_b32 v249, v117 offset:832
	ds_write_b32 v249, v118 offset:128
	ds_write_b32 v249, v119 offset:384
	ds_write_b32 v249, v120 offset:640
	ds_write_b32 v249, v121 offset:896
	ds_write_b32 v249, v122 offset:192
	ds_write_b32 v249, v123 offset:448
	ds_write_b32 v249, v124 offset:704
	ds_write_b32 v249, v125 offset:960
	ds_read_b32 v2, v250 offset:0
	ds_read_b32 v3, v250 offset:256
	ds_read_b32 v4, v250 offset:512
	ds_read_b32 v5, v250 offset:768
	ds_read_b32 v6, v250 offset:1024
	ds_read_b32 v7, v250 offset:1280
	ds_read_b32 v8, v250 offset:1536
	ds_read_b32 v9, v250 offset:1792
	ds_read_b32 v10, v250 offset:2048
	ds_read_b32 v11, v250 offset:2304
	ds_read_b32 v12, v250 offset:2560
	ds_read_b32 v13, v250 offset:2816
	ds_read_b32 v14, v250 offset:3072
	ds_read_b32 v15, v250 offset:3328
	ds_read_b32 v16, v250 offset:3584
	ds_read_b32 v17, v250 offset:3840
	v_mov_b32_e32 v241, 0x1a940
	ds_read_b128 v[22:25], v241 offset:272
	ds_read_b128 v[26:29], v241 offset:544
	ds_read_b128 v[30:33], v241 offset:816
	ds_read_b128 v[34:37], v241 offset:1088
	ds_read_b128 v[38:41], v241 offset:1360
	ds_read_b128 v[42:45], v241 offset:1632
	ds_read_b128 v[46:49], v241 offset:1904
	ds_read_b128 v[50:53], v241 offset:2176
	ds_read_b128 v[54:57], v241 offset:2448
	ds_read_b128 v[58:61], v241 offset:2720
	ds_read_b128 v[62:65], v241 offset:2992
	ds_read_b128 v[66:69], v241 offset:3264
	ds_read_b128 v[70:73], v241 offset:3536
	ds_read_b128 v[74:77], v241 offset:3808
	ds_read_b128 v[78:81], v241 offset:4080
	s_waitcnt lgkmcnt(0)
	ds_read_b128 v[82:85], v241 offset:1376
	ds_read_b128 v[86:89], v241 offset:1648
	ds_read_b128 v[90:93], v241 offset:1920
	ds_read_b128 v[96:99], v241 offset:2192
	ds_read_b128 v[100:103], v241 offset:2464
	ds_read_b128 v[110:113], v241 offset:2736
	ds_read_b128 v[114:117], v241 offset:3008
	ds_read_b128 v[118:121], v241 offset:3280
	ds_read_b128 v[122:125], v241 offset:3552
	ds_read_b128 v[126:129], v241 offset:3824
	ds_read_b128 v[130:133], v241 offset:4096
	v_fma_f32 v3, -v22, v2, v3
	v_fma_f32 v4, -v26, v2, v4
	v_fma_f32 v5, -v30, v2, v5
	v_fma_f32 v6, -v34, v2, v6
	v_fma_f32 v7, -v38, v2, v7
	v_fma_f32 v8, -v42, v2, v8
	v_fma_f32 v9, -v46, v2, v9
	v_fma_f32 v10, -v50, v2, v10
	v_fma_f32 v11, -v54, v2, v11
	v_fma_f32 v12, -v58, v2, v12
	v_fma_f32 v13, -v62, v2, v13
	v_fma_f32 v14, -v66, v2, v14
	v_fma_f32 v15, -v70, v2, v15
	v_fma_f32 v16, -v74, v2, v16
	v_fma_f32 v17, -v78, v2, v17
	v_fma_f32 v4, -v27, v3, v4
	v_fma_f32 v5, -v31, v3, v5
	v_fma_f32 v6, -v35, v3, v6
	v_fma_f32 v7, -v39, v3, v7
	v_fma_f32 v8, -v43, v3, v8
	v_fma_f32 v9, -v47, v3, v9
	v_fma_f32 v10, -v51, v3, v10
	v_fma_f32 v11, -v55, v3, v11
	v_fma_f32 v12, -v59, v3, v12
	v_fma_f32 v13, -v63, v3, v13
	v_fma_f32 v14, -v67, v3, v14
	v_fma_f32 v15, -v71, v3, v15
	v_fma_f32 v16, -v75, v3, v16
	v_fma_f32 v17, -v79, v3, v17
	v_fma_f32 v5, -v32, v4, v5
	v_fma_f32 v6, -v36, v4, v6
	v_fma_f32 v7, -v40, v4, v7
	v_fma_f32 v8, -v44, v4, v8
	v_fma_f32 v9, -v48, v4, v9
	v_fma_f32 v10, -v52, v4, v10
	v_fma_f32 v11, -v56, v4, v11
	v_fma_f32 v12, -v60, v4, v12
	v_fma_f32 v13, -v64, v4, v13
	v_fma_f32 v14, -v68, v4, v14
	v_fma_f32 v15, -v72, v4, v15
	v_fma_f32 v16, -v76, v4, v16
	v_fma_f32 v17, -v80, v4, v17
	v_fma_f32 v6, -v37, v5, v6
	v_fma_f32 v7, -v41, v5, v7
	v_fma_f32 v8, -v45, v5, v8
	v_fma_f32 v9, -v49, v5, v9
	v_fma_f32 v10, -v53, v5, v10
	v_fma_f32 v11, -v57, v5, v11
	v_fma_f32 v12, -v61, v5, v12
	v_fma_f32 v13, -v65, v5, v13
	v_fma_f32 v14, -v69, v5, v14
	v_fma_f32 v15, -v73, v5, v15
	v_fma_f32 v16, -v77, v5, v16
	v_fma_f32 v17, -v81, v5, v17
	s_waitcnt lgkmcnt(0)
; __device__ void prep_unit(unsigned char* lds, int bh, int n, const bf16_t* pc, const float* scal, const float* convw  , float alog, float dtb, unsigned char* unit, float* egl, unsigned* flag, unsigned fval) {
;     ...
;         for (int rb = 0; rb < 4; ++rb) {
;             typedef float f32x2v __attribute__((ext_vector_type(2)));
;             f32x2v sp[8];
; #pragma unroll
;             for (int q = 0; q < 8; ++q) { sp[q][0] = (16 * rb + 2 * q == c) ? 1.0f : 0.0f; sp[q][1] = (16 * rb + 2 * q + 1 == c) ? 1.0f : 0.0f; }
;             for (int j4 = 0; j4 < 4 * rb; ++j4) {
;                 const float t0 = Am[(4 * j4 + 0) * 68 + c], t1 = Am[(4 * j4 + 1) * 68 + c], t2 = Am[(4 * j4 + 2) * 68 + c], t3 = Am[(4 * j4 + 3) * 68 + c];
;                 const f32x2v T0 = {t0, t0}, T1 = {t1, t1}, T2 = {t2, t2}, T3 = {t3, t3};
; #pragma unroll
;                 for (int q = 0; q < 8; ++q) { const f32x4 a4 = *(const f32x4*)(AmV + (16 * rb + 2 * q) * 68 + 4 * j4), b4 = *(const f32x4*)(AmV + (16 * rb + 2 * q + 1) * 68 + 4 * j4);
;                     f32x2v acc2 = sp[q];
;                     acc2 -= (f32x2v){a4[0], b4[0]} * T0; acc2 -= (f32x2v){a4[1], b4[1]} * T1; acc2 -= (f32x2v){a4[2], b4[2]} * T2; acc2 -= (f32x2v){a4[3], b4[3]} * T3;
;                     sp[q] = acc2; }
;             }
;             float sx[16];
; #pragma unroll
;             for (int r = 0; r < 16; ++r) sx[r] = sp[r >> 1][r & 1];
; #pragma unroll
;             for (int r = 1; r < 16; ++r) {
; #pragma unroll
;                 for (int q4 = 0; q4 < (r + 3) / 4; ++q4) { const f32x4 a4 = *(const f32x4*)(AmV + (16 * rb + r) * 68 + 16 * rb + 4 * q4);
; #pragma unroll
;                     for (int jj = 0; jj < 4; ++jj) if (4 * q4 + jj < r) sx[r] -= a4[jj] * sx[4 * q4 + jj]; }
;             }
;             bf16_t* sf = stage + (rb * 2 + (c >> 5)) * 512 + ((c >> 3) & 3) * 128 + (c & 7);
; #pragma unroll
;             for (int r = 0; r < 16; r += 2) {
;                 Am[(16 * rb + r) * 68 + c] = sx[r]; Am[(16 * rb + r + 1) * 68 + c] = sx[r + 1];
;                 const unsigned ph = pack2(sx[r], sx[r + 1]);
;                 const unsigned pl = pack2(sx[r] - __uint_as_float(ph << 16), sx[r + 1] - __uint_as_float(ph & 0xffff0000u));
;                 sf[r * 8] = (bf16_t)(ph & 0xffffu); sf[(r + 1) * 8] = (bf16_t)(ph >> 16);
	ds_read_b128 v[134:137], v241 offset:2480
	ds_read_b128 v[138:141], v241 offset:2752
	ds_read_b128 v[142:145], v241 offset:3024
	ds_read_b128 v[146:149], v241 offset:3296
	ds_read_b128 v[150:153], v241 offset:3568
	ds_read_b128 v[158:161], v241 offset:3840
	ds_read_b128 v[162:165], v241 offset:4112
	v_fma_f32 v7, -v82, v6, v7
	v_fma_f32 v8, -v86, v6, v8
	v_fma_f32 v9, -v90, v6, v9
	v_fma_f32 v10, -v96, v6, v10
	v_fma_f32 v11, -v100, v6, v11
	v_fma_f32 v12, -v110, v6, v12
	v_fma_f32 v13, -v114, v6, v13
	v_fma_f32 v14, -v118, v6, v14
	v_fma_f32 v15, -v122, v6, v15
	v_fma_f32 v16, -v126, v6, v16
	v_fma_f32 v17, -v130, v6, v17
	v_fma_f32 v8, -v87, v7, v8
	v_fma_f32 v9, -v91, v7, v9
	v_fma_f32 v10, -v97, v7, v10
	v_fma_f32 v11, -v101, v7, v11
	v_fma_f32 v12, -v111, v7, v12
	v_fma_f32 v13, -v115, v7, v13
	v_fma_f32 v14, -v119, v7, v14
	v_fma_f32 v15, -v123, v7, v15
	v_fma_f32 v16, -v127, v7, v16
	v_fma_f32 v17, -v131, v7, v17
	v_fma_f32 v9, -v92, v8, v9
	v_fma_f32 v10, -v98, v8, v10
	v_fma_f32 v11, -v102, v8, v11
	v_fma_f32 v12, -v112, v8, v12
	v_fma_f32 v13, -v116, v8, v13
	v_fma_f32 v14, -v120, v8, v14
	v_fma_f32 v15, -v124, v8, v15
	v_fma_f32 v16, -v128, v8, v16
	v_fma_f32 v17, -v132, v8, v17
	v_fma_f32 v10, -v99, v9, v10
	v_fma_f32 v11, -v103, v9, v11
	v_fma_f32 v12, -v113, v9, v12
	v_fma_f32 v13, -v117, v9, v13
	v_fma_f32 v14, -v121, v9, v14
	v_fma_f32 v15, -v125, v9, v15
	v_fma_f32 v16, -v129, v9, v16
	v_fma_f32 v17, -v133, v9, v17
	s_waitcnt lgkmcnt(0)
	ds_read_b128 v[166:169], v241 offset:3584
	ds_read_b128 v[182:185], v241 offset:3856
	ds_read_b128 v[186:189], v241 offset:4128
	v_fma_f32 v11, -v134, v10, v11
	v_fma_f32 v12, -v138, v10, v12
	v_fma_f32 v13, -v142, v10, v13
	v_fma_f32 v14, -v146, v10, v14
	v_fma_f32 v15, -v150, v10, v15
	v_fma_f32 v16, -v158, v10, v16
	v_fma_f32 v17, -v162, v10, v17
	v_fma_f32 v12, -v139, v11, v12
	v_fma_f32 v13, -v143, v11, v13
	v_fma_f32 v14, -v147, v11, v14
	v_fma_f32 v15, -v151, v11, v15
	v_fma_f32 v16, -v159, v11, v16
	v_fma_f32 v17, -v163, v11, v17
	v_fma_f32 v13, -v144, v12, v13
	v_fma_f32 v14, -v148, v12, v14
	v_fma_f32 v15, -v152, v12, v15
	v_fma_f32 v16, -v160, v12, v16
	v_fma_f32 v17, -v164, v12, v17
	v_fma_f32 v14, -v149, v13, v14
	v_fma_f32 v15, -v153, v13, v15
	v_fma_f32 v16, -v161, v13, v16
	v_fma_f32 v17, -v165, v13, v17
	s_waitcnt lgkmcnt(0)
	v_fma_f32 v15, -v166, v14, v15
	v_fma_f32 v16, -v182, v14, v16
	v_fma_f32 v17, -v186, v14, v17
	v_fma_f32 v16, -v183, v15, v16
	v_fma_f32 v17, -v187, v15, v17
	v_fma_f32 v17, -v188, v16, v17
	ds_write_b32 v240, v2 offset:4352
	ds_write_b32 v240, v3 offset:4624
	ds_write_b32 v240, v4 offset:4896
	ds_write_b32 v240, v5 offset:5168
	ds_write_b32 v240, v6 offset:5440
	ds_write_b32 v240, v7 offset:5712
	ds_write_b32 v240, v8 offset:5984
	ds_write_b32 v240, v9 offset:6256
	ds_write_b32 v240, v10 offset:6528
	ds_write_b32 v240, v11 offset:6800
	ds_write_b32 v240, v12 offset:7072
	ds_write_b32 v240, v13 offset:7344
	ds_write_b32 v240, v14 offset:7616
	ds_write_b32 v240, v15 offset:7888
	ds_write_b32 v240, v16 offset:8160
	ds_write_b32 v240, v17 offset:8432
	v_mov_b32_e32 v110, 0
	v_mov_b32_e32 v111, 0
	v_mov_b32_e32 v112, 0
	v_mov_b32_e32 v113, 0
	v_mov_b32_e32 v114, 0
	v_mov_b32_e32 v115, 0
	v_mov_b32_e32 v116, 0
	v_mov_b32_e32 v117, 0
	v_cmp_eq_u32_e64 s[2:3], 0, v251
	v_cmp_eq_u32_e64 s[4:5], 1, v251
	v_cmp_eq_u32_e64 s[8:9], 2, v251
	v_cmp_eq_u32_e64 s[10:11], 3, v251
	v_mov_b32_e32 v122, 0
	v_mov_b32_e32 v123, 0
	v_mov_b32_e32 v124, 0
	v_mov_b32_e32 v125, 0
	v_cndmask_b32_e64 v118, 0, 1.0, s[2:3]
	v_cndmask_b32_e64 v119, 0, 1.0, s[4:5]
	v_cndmask_b32_e64 v120, 0, 1.0, s[8:9]
	v_cndmask_b32_e64 v121, 0, 1.0, s[10:11]
	ds_read_b128 v[126:129], v246 offset:8704
	ds_read_b32 v130, v247 offset:0
	ds_read_b32 v131, v247 offset:272
	ds_read_b32 v132, v247 offset:544
	ds_read_b32 v133, v247 offset:816
	s_waitcnt lgkmcnt(4)
	v_xor_b32_e32 v126, 0x80000000, v126
	v_xor_b32_e32 v127, 0x80000000, v127
	v_xor_b32_e32 v128, 0x80000000, v128
	v_xor_b32_e32 v129, 0x80000000, v129
	s_waitcnt lgkmcnt(0)
	s_nop 1
	v_mfma_f32_16x16x4_f32 v[110:113], v126, v130, v[110:113]
	v_mfma_f32_16x16x4_f32 v[110:113], v127, v131, v[110:113]
	v_mfma_f32_16x16x4_f32 v[110:113], v128, v132, v[110:113]
	v_mfma_f32_16x16x4_f32 v[110:113], v129, v133, v[110:113]
	s_nop 7
	ds_read_b128 v[126:129], v246 offset:8768
	ds_read_b32 v130, v247 offset:4352
	ds_read_b32 v131, v247 offset:4624
	ds_read_b32 v132, v247 offset:4896
	ds_read_b32 v133, v247 offset:5168
	ds_read_b32 v134, v247 offset:4416
	ds_read_b32 v135, v247 offset:4688
	ds_read_b32 v136, v247 offset:4960
	ds_read_b32 v137, v247 offset:5232
	s_waitcnt lgkmcnt(8)
	v_xor_b32_e32 v126, 0x80000000, v126
	v_xor_b32_e32 v127, 0x80000000, v127
	v_xor_b32_e32 v128, 0x80000000, v128
	v_xor_b32_e32 v129, 0x80000000, v129
	s_waitcnt lgkmcnt(0)
; __device__ void prep_unit(unsigned char* lds, int bh, int n, const bf16_t* pc, const float* scal, const float* convw  , float alog, float dtb, unsigned char* unit, float* egl, unsigned* flag, unsigned fval) {
;     ...
;         for (int rb = 0; rb < 4; ++rb) {
;             typedef float f32x2v __attribute__((ext_vector_type(2)));
;             f32x2v sp[8];
; #pragma unroll
;             for (int q = 0; q < 8; ++q) { sp[q][0] = (16 * rb + 2 * q == c) ? 1.0f : 0.0f; sp[q][1] = (16 * rb + 2 * q + 1 == c) ? 1.0f : 0.0f; }
;             for (int j4 = 0; j4 < 4 * rb; ++j4) {
;                 const float t0 = Am[(4 * j4 + 0) * 68 + c], t1 = Am[(4 * j4 + 1) * 68 + c], t2 = Am[(4 * j4 + 2) * 68 + c], t3 = Am[(4 * j4 + 3) * 68 + c];
;                 const f32x2v T0 = {t0, t0}, T1 = {t1, t1}, T2 = {t2, t2}, T3 = {t3, t3};
; #pragma unroll
;                 for (int q = 0; q < 8; ++q) { const f32x4 a4 = *(const f32x4*)(AmV + (16 * rb + 2 * q) * 68 + 4 * j4), b4 = *(const f32x4*)(AmV + (16 * rb + 2 * q + 1) * 68 + 4 * j4);
;                     f32x2v acc2 = sp[q];
;                     acc2 -= (f32x2v){a4[0], b4[0]} * T0; acc2 -= (f32x2v){a4[1], b4[1]} * T1; acc2 -= (f32x2v){a4[2], b4[2]} * T2; acc2 -= (f32x2v){a4[3], b4[3]} * T3;
;                     sp[q] = acc2; }
;             }
;             float sx[16];
; #pragma unroll
;             for (int r = 0; r < 16; ++r) sx[r] = sp[r >> 1][r & 1];
; #pragma unroll
;             for (int r = 1; r < 16; ++r) {
; #pragma unroll
;                 for (int q4 = 0; q4 < (r + 3) / 4; ++q4) { const f32x4 a4 = *(const f32x4*)(AmV + (16 * rb + r) * 68 + 16 * rb + 4 * q4);
; #pragma unroll
;                     for (int jj = 0; jj < 4; ++jj) if (4 * q4 + jj < r) sx[r] -= a4[jj] * sx[4 * q4 + jj]; }
;             }
	s_nop 1
	v_mfma_f32_16x16x4_f32 v[110:113], v126, v130, v[110:113]
	v_mfma_f32_16x16x4_f32 v[114:117], v126, v134, v[114:117]
	v_mfma_f32_16x16x4_f32 v[110:113], v127, v131, v[110:113]
	v_mfma_f32_16x16x4_f32 v[114:117], v127, v135, v[114:117]
	v_mfma_f32_16x16x4_f32 v[110:113], v128, v132, v[110:113]
	v_mfma_f32_16x16x4_f32 v[114:117], v128, v136, v[114:117]
	v_mfma_f32_16x16x4_f32 v[110:113], v129, v133, v[110:113]
	v_mfma_f32_16x16x4_f32 v[114:117], v129, v137, v[114:117]
	s_nop 7
	s_nop 3
	ds_write_b32 v249, v110 offset:0
	ds_write_b32 v249, v111 offset:256
	ds_write_b32 v249, v112 offset:512
	ds_write_b32 v249, v113 offset:768
	ds_write_b32 v249, v114 offset:64
	ds_write_b32 v249, v115 offset:320
	ds_write_b32 v249, v116 offset:576
	ds_write_b32 v249, v117 offset:832
	ds_write_b32 v249, v118 offset:128
	ds_write_b32 v249, v119 offset:384
	ds_write_b32 v249, v120 offset:640
	ds_write_b32 v249, v121 offset:896
	ds_write_b32 v249, v122 offset:192
	ds_write_b32 v249, v123 offset:448
	ds_write_b32 v249, v124 offset:704
	ds_write_b32 v249, v125 offset:960
	ds_read_b32 v2, v250 offset:0
	ds_read_b32 v3, v250 offset:256
	ds_read_b32 v4, v250 offset:512
	ds_read_b32 v5, v250 offset:768
	ds_read_b32 v6, v250 offset:1024
	ds_read_b32 v7, v250 offset:1280
	ds_read_b32 v8, v250 offset:1536
	ds_read_b32 v9, v250 offset:1792
	ds_read_b32 v10, v250 offset:2048
	ds_read_b32 v11, v250 offset:2304
	ds_read_b32 v12, v250 offset:2560
	ds_read_b32 v13, v250 offset:2816
	ds_read_b32 v14, v250 offset:3072
	ds_read_b32 v15, v250 offset:3328
	ds_read_b32 v16, v250 offset:3584
	ds_read_b32 v17, v250 offset:3840
	v_mov_b32_e32 v241, 0x1ba80
	ds_read_b128 v[22:25], v241 offset:272
	ds_read_b128 v[26:29], v241 offset:544
	ds_read_b128 v[30:33], v241 offset:816
	ds_read_b128 v[34:37], v241 offset:1088
	ds_read_b128 v[38:41], v241 offset:1360
	ds_read_b128 v[42:45], v241 offset:1632
	ds_read_b128 v[46:49], v241 offset:1904
	ds_read_b128 v[50:53], v241 offset:2176
	ds_read_b128 v[54:57], v241 offset:2448
	ds_read_b128 v[58:61], v241 offset:2720
	ds_read_b128 v[62:65], v241 offset:2992
	ds_read_b128 v[66:69], v241 offset:3264
	ds_read_b128 v[70:73], v241 offset:3536
	ds_read_b128 v[74:77], v241 offset:3808
	ds_read_b128 v[78:81], v241 offset:4080
	s_waitcnt lgkmcnt(0)
	ds_read_b128 v[82:85], v241 offset:1376
	ds_read_b128 v[86:89], v241 offset:1648
	ds_read_b128 v[90:93], v241 offset:1920
	ds_read_b128 v[96:99], v241 offset:2192
	ds_read_b128 v[100:103], v241 offset:2464
	ds_read_b128 v[110:113], v241 offset:2736
	ds_read_b128 v[114:117], v241 offset:3008
	ds_read_b128 v[118:121], v241 offset:3280
	ds_read_b128 v[122:125], v241 offset:3552
	ds_read_b128 v[126:129], v241 offset:3824
	ds_read_b128 v[130:133], v241 offset:4096
	v_fma_f32 v3, -v22, v2, v3
	v_fma_f32 v4, -v26, v2, v4
	v_fma_f32 v5, -v30, v2, v5
	v_fma_f32 v6, -v34, v2, v6
	v_fma_f32 v7, -v38, v2, v7
	v_fma_f32 v8, -v42, v2, v8
	v_fma_f32 v9, -v46, v2, v9
	v_fma_f32 v10, -v50, v2, v10
	v_fma_f32 v11, -v54, v2, v11
	v_fma_f32 v12, -v58, v2, v12
	v_fma_f32 v13, -v62, v2, v13
	v_fma_f32 v14, -v66, v2, v14
	v_fma_f32 v15, -v70, v2, v15
	v_fma_f32 v16, -v74, v2, v16
	v_fma_f32 v17, -v78, v2, v17
	v_fma_f32 v4, -v27, v3, v4
	v_fma_f32 v5, -v31, v3, v5
	v_fma_f32 v6, -v35, v3, v6
	v_fma_f32 v7, -v39, v3, v7
	v_fma_f32 v8, -v43, v3, v8
	v_fma_f32 v9, -v47, v3, v9
	v_fma_f32 v10, -v51, v3, v10
	v_fma_f32 v11, -v55, v3, v11
	v_fma_f32 v12, -v59, v3, v12
	v_fma_f32 v13, -v63, v3, v13
	v_fma_f32 v14, -v67, v3, v14
	v_fma_f32 v15, -v71, v3, v15
	v_fma_f32 v16, -v75, v3, v16
	v_fma_f32 v17, -v79, v3, v17
	v_fma_f32 v5, -v32, v4, v5
	v_fma_f32 v6, -v36, v4, v6
	v_fma_f32 v7, -v40, v4, v7
	v_fma_f32 v8, -v44, v4, v8
	v_fma_f32 v9, -v48, v4, v9
	v_fma_f32 v10, -v52, v4, v10
	v_fma_f32 v11, -v56, v4, v11
	v_fma_f32 v12, -v60, v4, v12
	v_fma_f32 v13, -v64, v4, v13
	v_fma_f32 v14, -v68, v4, v14
	v_fma_f32 v15, -v72, v4, v15
	v_fma_f32 v16, -v76, v4, v16
	v_fma_f32 v17, -v80, v4, v17
	v_fma_f32 v6, -v37, v5, v6
	v_fma_f32 v7, -v41, v5, v7
	v_fma_f32 v8, -v45, v5, v8
	v_fma_f32 v9, -v49, v5, v9
	v_fma_f32 v10, -v53, v5, v10
	v_fma_f32 v11, -v57, v5, v11
	v_fma_f32 v12, -v61, v5, v12
	v_fma_f32 v13, -v65, v5, v13
	v_fma_f32 v14, -v69, v5, v14
	v_fma_f32 v15, -v73, v5, v15
	v_fma_f32 v16, -v77, v5, v16
	v_fma_f32 v17, -v81, v5, v17
	s_waitcnt lgkmcnt(0)
	ds_read_b128 v[134:137], v241 offset:2480
	ds_read_b128 v[138:141], v241 offset:2752
	ds_read_b128 v[142:145], v241 offset:3024
	ds_read_b128 v[146:149], v241 offset:3296
	ds_read_b128 v[150:153], v241 offset:3568
	ds_read_b128 v[158:161], v241 offset:3840
	ds_read_b128 v[162:165], v241 offset:4112
	v_fma_f32 v7, -v82, v6, v7
	v_fma_f32 v8, -v86, v6, v8
	v_fma_f32 v9, -v90, v6, v9
	v_fma_f32 v10, -v96, v6, v10
	v_fma_f32 v11, -v100, v6, v11
	v_fma_f32 v12, -v110, v6, v12
	v_fma_f32 v13, -v114, v6, v13
	v_fma_f32 v14, -v118, v6, v14
	v_fma_f32 v15, -v122, v6, v15
	v_fma_f32 v16, -v126, v6, v16
	v_fma_f32 v17, -v130, v6, v17
	v_fma_f32 v8, -v87, v7, v8
	v_fma_f32 v9, -v91, v7, v9
	v_fma_f32 v10, -v97, v7, v10
	v_fma_f32 v11, -v101, v7, v11
	v_fma_f32 v12, -v111, v7, v12
	v_fma_f32 v13, -v115, v7, v13
	v_fma_f32 v14, -v119, v7, v14
	v_fma_f32 v15, -v123, v7, v15
	v_fma_f32 v16, -v127, v7, v16
	v_fma_f32 v17, -v131, v7, v17
	v_fma_f32 v9, -v92, v8, v9
	v_fma_f32 v10, -v98, v8, v10
	v_fma_f32 v11, -v102, v8, v11
	v_fma_f32 v12, -v112, v8, v12
	v_fma_f32 v13, -v116, v8, v13
	v_fma_f32 v14, -v120, v8, v14
	v_fma_f32 v15, -v124, v8, v15
	v_fma_f32 v16, -v128, v8, v16
	v_fma_f32 v17, -v132, v8, v17
	v_fma_f32 v10, -v99, v9, v10
	v_fma_f32 v11, -v103, v9, v11
	v_fma_f32 v12, -v113, v9, v12
	v_fma_f32 v13, -v117, v9, v13
	v_fma_f32 v14, -v121, v9, v14
	v_fma_f32 v15, -v125, v9, v15
	v_fma_f32 v16, -v129, v9, v16
	v_fma_f32 v17, -v133, v9, v17
	s_waitcnt lgkmcnt(0)
; __device__ void prep_unit(unsigned char* lds, int bh, int n, const bf16_t* pc, const float* scal, const float* convw  , float alog, float dtb, unsigned char* unit, float* egl, unsigned* flag, unsigned fval) {
;     ...
;         for (int rb = 0; rb < 4; ++rb) {
;             typedef float f32x2v __attribute__((ext_vector_type(2)));
;             f32x2v sp[8];
; #pragma unroll
;             for (int q = 0; q < 8; ++q) { sp[q][0] = (16 * rb + 2 * q == c) ? 1.0f : 0.0f; sp[q][1] = (16 * rb + 2 * q + 1 == c) ? 1.0f : 0.0f; }
;             for (int j4 = 0; j4 < 4 * rb; ++j4) {
;                 const float t0 = Am[(4 * j4 + 0) * 68 + c], t1 = Am[(4 * j4 + 1) * 68 + c], t2 = Am[(4 * j4 + 2) * 68 + c], t3 = Am[(4 * j4 + 3) * 68 + c];
;                 const f32x2v T0 = {t0, t0}, T1 = {t1, t1}, T2 = {t2, t2}, T3 = {t3, t3};
; #pragma unroll
;                 for (int q = 0; q < 8; ++q) { const f32x4 a4 = *(const f32x4*)(AmV + (16 * rb + 2 * q) * 68 + 4 * j4), b4 = *(const f32x4*)(AmV + (16 * rb + 2 * q + 1) * 68 + 4 * j4);
;                     f32x2v acc2 = sp[q];
;                     acc2 -= (f32x2v){a4[0], b4[0]} * T0; acc2 -= (f32x2v){a4[1], b4[1]} * T1; acc2 -= (f32x2v){a4[2], b4[2]} * T2; acc2 -= (f32x2v){a4[3], b4[3]} * T3;
;                     sp[q] = acc2; }
;             }
;             float sx[16];
; #pragma unroll
;             for (int r = 0; r < 16; ++r) sx[r] = sp[r >> 1][r & 1];
; #pragma unroll
;             for (int r = 1; r < 16; ++r) {
; #pragma unroll
;                 for (int q4 = 0; q4 < (r + 3) / 4; ++q4) { const f32x4 a4 = *(const f32x4*)(AmV + (16 * rb + r) * 68 + 16 * rb + 4 * q4);
; #pragma unroll
;                     for (int jj = 0; jj < 4; ++jj) if (4 * q4 + jj < r) sx[r] -= a4[jj] * sx[4 * q4 + jj]; }
;             }
;             bf16_t* sf = stage + (rb * 2 + (c >> 5)) * 512 + ((c >> 3) & 3) * 128 + (c & 7);
; #pragma unroll
;             for (int r = 0; r < 16; r += 2) {
;                 Am[(16 * rb + r) * 68 + c] = sx[r]; Am[(16 * rb + r + 1) * 68 + c] = sx[r + 1];
;                 const unsigned ph = pack2(sx[r], sx[r + 1]);
;                 const unsigned pl = pack2(sx[r] - __uint_as_float(ph << 16), sx[r + 1] - __uint_as_float(ph & 0xffff0000u));
;                 sf[r * 8] = (bf16_t)(ph & 0xffffu); sf[(r + 1) * 8] = (bf16_t)(ph >> 16);
	ds_read_b128 v[166:169], v241 offset:3584
	ds_read_b128 v[182:185], v241 offset:3856
	ds_read_b128 v[186:189], v241 offset:4128
	v_fma_f32 v11, -v134, v10, v11
	v_fma_f32 v12, -v138, v10, v12
	v_fma_f32 v13, -v142, v10, v13
	v_fma_f32 v14, -v146, v10, v14
	v_fma_f32 v15, -v150, v10, v15
	v_fma_f32 v16, -v158, v10, v16
	v_fma_f32 v17, -v162, v10, v17
	v_fma_f32 v12, -v139, v11, v12
	v_fma_f32 v13, -v143, v11, v13
	v_fma_f32 v14, -v147, v11, v14
	v_fma_f32 v15, -v151, v11, v15
	v_fma_f32 v16, -v159, v11, v16
	v_fma_f32 v17, -v163, v11, v17
	v_fma_f32 v13, -v144, v12, v13
	v_fma_f32 v14, -v148, v12, v14
	v_fma_f32 v15, -v152, v12, v15
	v_fma_f32 v16, -v160, v12, v16
	v_fma_f32 v17, -v164, v12, v17
	v_fma_f32 v14, -v149, v13, v14
	v_fma_f32 v15, -v153, v13, v15
	v_fma_f32 v16, -v161, v13, v16
	v_fma_f32 v17, -v165, v13, v17
	s_waitcnt lgkmcnt(0)
	v_fma_f32 v15, -v166, v14, v15
	v_fma_f32 v16, -v182, v14, v16
	v_fma_f32 v17, -v186, v14, v17
	v_fma_f32 v16, -v183, v15, v16
	v_fma_f32 v17, -v187, v15, v17
	v_fma_f32 v17, -v188, v16, v17
	ds_write_b32 v240, v2 offset:8704
	ds_write_b32 v240, v3 offset:8976
	ds_write_b32 v240, v4 offset:9248
	ds_write_b32 v240, v5 offset:9520
	ds_write_b32 v240, v6 offset:9792
	ds_write_b32 v240, v7 offset:10064
	ds_write_b32 v240, v8 offset:10336
	ds_write_b32 v240, v9 offset:10608
	ds_write_b32 v240, v10 offset:10880
	ds_write_b32 v240, v11 offset:11152
	ds_write_b32 v240, v12 offset:11424
	ds_write_b32 v240, v13 offset:11696
	ds_write_b32 v240, v14 offset:11968
	ds_write_b32 v240, v15 offset:12240
	ds_write_b32 v240, v16 offset:12512
	ds_write_b32 v240, v17 offset:12784
	v_mov_b32_e32 v110, 0
	v_mov_b32_e32 v111, 0
	v_mov_b32_e32 v112, 0
	v_mov_b32_e32 v113, 0
	v_mov_b32_e32 v114, 0
	v_mov_b32_e32 v115, 0
	v_mov_b32_e32 v116, 0
	v_mov_b32_e32 v117, 0
	v_mov_b32_e32 v118, 0
	v_mov_b32_e32 v119, 0
	v_mov_b32_e32 v120, 0
	v_mov_b32_e32 v121, 0
	v_cmp_eq_u32_e64 s[2:3], 0, v251
	v_cmp_eq_u32_e64 s[4:5], 1, v251
	v_cmp_eq_u32_e64 s[8:9], 2, v251
	v_cmp_eq_u32_e64 s[10:11], 3, v251
	v_cndmask_b32_e64 v122, 0, 1.0, s[2:3]
	v_cndmask_b32_e64 v123, 0, 1.0, s[4:5]
	v_cndmask_b32_e64 v124, 0, 1.0, s[8:9]
	v_cndmask_b32_e64 v125, 0, 1.0, s[10:11]
	ds_read_b128 v[126:129], v246 offset:13056
	ds_read_b32 v130, v247 offset:0
	ds_read_b32 v131, v247 offset:272
	ds_read_b32 v132, v247 offset:544
	ds_read_b32 v133, v247 offset:816
	s_waitcnt lgkmcnt(4)
	v_xor_b32_e32 v126, 0x80000000, v126
	v_xor_b32_e32 v127, 0x80000000, v127
	v_xor_b32_e32 v128, 0x80000000, v128
	v_xor_b32_e32 v129, 0x80000000, v129
	s_waitcnt lgkmcnt(0)
	s_nop 1
	v_mfma_f32_16x16x4_f32 v[110:113], v126, v130, v[110:113]
	v_mfma_f32_16x16x4_f32 v[110:113], v127, v131, v[110:113]
	v_mfma_f32_16x16x4_f32 v[110:113], v128, v132, v[110:113]
	v_mfma_f32_16x16x4_f32 v[110:113], v129, v133, v[110:113]
	s_nop 7
	ds_read_b128 v[126:129], v246 offset:13120
	ds_read_b32 v130, v247 offset:4352
	ds_read_b32 v131, v247 offset:4624
	ds_read_b32 v132, v247 offset:4896
	ds_read_b32 v133, v247 offset:5168
	ds_read_b32 v134, v247 offset:4416
	ds_read_b32 v135, v247 offset:4688
	ds_read_b32 v136, v247 offset:4960
	ds_read_b32 v137, v247 offset:5232
	s_waitcnt lgkmcnt(8)
	v_xor_b32_e32 v126, 0x80000000, v126
	v_xor_b32_e32 v127, 0x80000000, v127
	v_xor_b32_e32 v128, 0x80000000, v128
	v_xor_b32_e32 v129, 0x80000000, v129
	s_waitcnt lgkmcnt(0)
	s_nop 1
	v_mfma_f32_16x16x4_f32 v[110:113], v126, v130, v[110:113]
	v_mfma_f32_16x16x4_f32 v[114:117], v126, v134, v[114:117]
	v_mfma_f32_16x16x4_f32 v[110:113], v127, v131, v[110:113]
	v_mfma_f32_16x16x4_f32 v[114:117], v127, v135, v[114:117]
	v_mfma_f32_16x16x4_f32 v[110:113], v128, v132, v[110:113]
	v_mfma_f32_16x16x4_f32 v[114:117], v128, v136, v[114:117]
	v_mfma_f32_16x16x4_f32 v[110:113], v129, v133, v[110:113]
	v_mfma_f32_16x16x4_f32 v[114:117], v129, v137, v[114:117]
	s_nop 7
	ds_read_b128 v[126:129], v246 offset:13184
	ds_read_b32 v130, v247 offset:8704
	ds_read_b32 v131, v247 offset:8976
	ds_read_b32 v132, v247 offset:9248
	ds_read_b32 v133, v247 offset:9520
	ds_read_b32 v134, v247 offset:8768
	ds_read_b32 v135, v247 offset:9040
	ds_read_b32 v136, v247 offset:9312
	ds_read_b32 v137, v247 offset:9584
	ds_read_b32 v138, v247 offset:8832
	ds_read_b32 v139, v247 offset:9104
	ds_read_b32 v140, v247 offset:9376
	ds_read_b32 v141, v247 offset:9648
	s_waitcnt lgkmcnt(12)
	v_xor_b32_e32 v126, 0x80000000, v126
	v_xor_b32_e32 v127, 0x80000000, v127
	v_xor_b32_e32 v128, 0x80000000, v128
	v_xor_b32_e32 v129, 0x80000000, v129
	s_waitcnt lgkmcnt(0)
; __device__ void prep_unit(unsigned char* lds, int bh, int n, const bf16_t* pc, const float* scal, const float* convw  , float alog, float dtb, unsigned char* unit, float* egl, unsigned* flag, unsigned fval) {
;     ...
;         for (int rb = 0; rb < 4; ++rb) {
;             typedef float f32x2v __attribute__((ext_vector_type(2)));
;             f32x2v sp[8];
; #pragma unroll
;             for (int q = 0; q < 8; ++q) { sp[q][0] = (16 * rb + 2 * q == c) ? 1.0f : 0.0f; sp[q][1] = (16 * rb + 2 * q + 1 == c) ? 1.0f : 0.0f; }
;             for (int j4 = 0; j4 < 4 * rb; ++j4) {
;                 const float t0 = Am[(4 * j4 + 0) * 68 + c], t1 = Am[(4 * j4 + 1) * 68 + c], t2 = Am[(4 * j4 + 2) * 68 + c], t3 = Am[(4 * j4 + 3) * 68 + c];
;                 const f32x2v T0 = {t0, t0}, T1 = {t1, t1}, T2 = {t2, t2}, T3 = {t3, t3};
; #pragma unroll
;                 for (int q = 0; q < 8; ++q) { const f32x4 a4 = *(const f32x4*)(AmV + (16 * rb + 2 * q) * 68 + 4 * j4), b4 = *(const f32x4*)(AmV + (16 * rb + 2 * q + 1) * 68 + 4 * j4);
;                     f32x2v acc2 = sp[q];
;                     acc2 -= (f32x2v){a4[0], b4[0]} * T0; acc2 -= (f32x2v){a4[1], b4[1]} * T1; acc2 -= (f32x2v){a4[2], b4[2]} * T2; acc2 -= (f32x2v){a4[3], b4[3]} * T3;
;                     sp[q] = acc2; }
;             }
;             float sx[16];
; #pragma unroll
;             for (int r = 0; r < 16; ++r) sx[r] = sp[r >> 1][r & 1];
; #pragma unroll
;             for (int r = 1; r < 16; ++r) {
; #pragma unroll
;                 for (int q4 = 0; q4 < (r + 3) / 4; ++q4) { const f32x4 a4 = *(const f32x4*)(AmV + (16 * rb + r) * 68 + 16 * rb + 4 * q4);
; #pragma unroll
;                     for (int jj = 0; jj < 4; ++jj) if (4 * q4 + jj < r) sx[r] -= a4[jj] * sx[4 * q4 + jj]; }
;             }
;             bf16_t* sf = stage + (rb * 2 + (c >> 5)) * 512 + ((c >> 3) & 3) * 128 + (c & 7);
; #pragma unroll
;             for (int r = 0; r < 16; r += 2) {
;                 Am[(16 * rb + r) * 68 + c] = sx[r]; Am[(16 * rb + r + 1) * 68 + c] = sx[r + 1];
;                 const unsigned ph = pack2(sx[r], sx[r + 1]);
;                 const unsigned pl = pack2(sx[r] - __uint_as_float(ph << 16), sx[r + 1] - __uint_as_float(ph & 0xffff0000u));
;                 sf[r * 8] = (bf16_t)(ph & 0xffffu); sf[(r + 1) * 8] = (bf16_t)(ph >> 16);
	s_nop 1
	v_mfma_f32_16x16x4_f32 v[110:113], v126, v130, v[110:113]
	v_mfma_f32_16x16x4_f32 v[114:117], v126, v134, v[114:117]
	v_mfma_f32_16x16x4_f32 v[118:121], v126, v138, v[118:121]
	v_mfma_f32_16x16x4_f32 v[110:113], v127, v131, v[110:113]
	v_mfma_f32_16x16x4_f32 v[114:117], v127, v135, v[114:117]
	v_mfma_f32_16x16x4_f32 v[118:121], v127, v139, v[118:121]
	v_mfma_f32_16x16x4_f32 v[110:113], v128, v132, v[110:113]
	v_mfma_f32_16x16x4_f32 v[114:117], v128, v136, v[114:117]
	v_mfma_f32_16x16x4_f32 v[118:121], v128, v140, v[118:121]
	v_mfma_f32_16x16x4_f32 v[110:113], v129, v133, v[110:113]
	v_mfma_f32_16x16x4_f32 v[114:117], v129, v137, v[114:117]
	v_mfma_f32_16x16x4_f32 v[118:121], v129, v141, v[118:121]
	s_nop 7
	s_nop 3
	ds_write_b32 v249, v110 offset:0
	ds_write_b32 v249, v111 offset:256
	ds_write_b32 v249, v112 offset:512
	ds_write_b32 v249, v113 offset:768
	ds_write_b32 v249, v114 offset:64
	ds_write_b32 v249, v115 offset:320
	ds_write_b32 v249, v116 offset:576
	ds_write_b32 v249, v117 offset:832
	ds_write_b32 v249, v118 offset:128
	ds_write_b32 v249, v119 offset:384
	ds_write_b32 v249, v120 offset:640
	ds_write_b32 v249, v121 offset:896
	ds_write_b32 v249, v122 offset:192
	ds_write_b32 v249, v123 offset:448
	ds_write_b32 v249, v124 offset:704
	ds_write_b32 v249, v125 offset:960
	ds_read_b32 v2, v250 offset:0
	ds_read_b32 v3, v250 offset:256
	ds_read_b32 v4, v250 offset:512
	ds_read_b32 v5, v250 offset:768
	ds_read_b32 v6, v250 offset:1024
	ds_read_b32 v7, v250 offset:1280
	ds_read_b32 v8, v250 offset:1536
	ds_read_b32 v9, v250 offset:1792
	ds_read_b32 v10, v250 offset:2048
	ds_read_b32 v11, v250 offset:2304
	ds_read_b32 v12, v250 offset:2560
	ds_read_b32 v13, v250 offset:2816
	ds_read_b32 v14, v250 offset:3072
	ds_read_b32 v15, v250 offset:3328
	ds_read_b32 v16, v250 offset:3584
	ds_read_b32 v17, v250 offset:3840
	v_mov_b32_e32 v241, 0x1cbc0
	ds_read_b128 v[22:25], v241 offset:272
	ds_read_b128 v[26:29], v241 offset:544
	ds_read_b128 v[30:33], v241 offset:816
	ds_read_b128 v[34:37], v241 offset:1088
	ds_read_b128 v[38:41], v241 offset:1360
	ds_read_b128 v[42:45], v241 offset:1632
	ds_read_b128 v[46:49], v241 offset:1904
	ds_read_b128 v[50:53], v241 offset:2176
	ds_read_b128 v[54:57], v241 offset:2448
	ds_read_b128 v[58:61], v241 offset:2720
	ds_read_b128 v[62:65], v241 offset:2992
	ds_read_b128 v[66:69], v241 offset:3264
	ds_read_b128 v[70:73], v241 offset:3536
	ds_read_b128 v[74:77], v241 offset:3808
	ds_read_b128 v[78:81], v241 offset:4080
	s_waitcnt lgkmcnt(0)
	ds_read_b128 v[82:85], v241 offset:1376
	ds_read_b128 v[86:89], v241 offset:1648
	ds_read_b128 v[90:93], v241 offset:1920
	ds_read_b128 v[96:99], v241 offset:2192
	ds_read_b128 v[100:103], v241 offset:2464
	ds_read_b128 v[110:113], v241 offset:2736
	ds_read_b128 v[114:117], v241 offset:3008
	ds_read_b128 v[118:121], v241 offset:3280
	ds_read_b128 v[122:125], v241 offset:3552
	ds_read_b128 v[126:129], v241 offset:3824
	ds_read_b128 v[130:133], v241 offset:4096
	v_fma_f32 v3, -v22, v2, v3
	v_fma_f32 v4, -v26, v2, v4
	v_fma_f32 v5, -v30, v2, v5
	v_fma_f32 v6, -v34, v2, v6
	v_fma_f32 v7, -v38, v2, v7
	v_fma_f32 v8, -v42, v2, v8
	v_fma_f32 v9, -v46, v2, v9
	v_fma_f32 v10, -v50, v2, v10
	v_fma_f32 v11, -v54, v2, v11
	v_fma_f32 v12, -v58, v2, v12
	v_fma_f32 v13, -v62, v2, v13
	v_fma_f32 v14, -v66, v2, v14
	v_fma_f32 v15, -v70, v2, v15
	v_fma_f32 v16, -v74, v2, v16
	v_fma_f32 v17, -v78, v2, v17
	v_fma_f32 v4, -v27, v3, v4
	v_fma_f32 v5, -v31, v3, v5
	v_fma_f32 v6, -v35, v3, v6
	v_fma_f32 v7, -v39, v3, v7
	v_fma_f32 v8, -v43, v3, v8
	v_fma_f32 v9, -v47, v3, v9
	v_fma_f32 v10, -v51, v3, v10
	v_fma_f32 v11, -v55, v3, v11
	v_fma_f32 v12, -v59, v3, v12
	v_fma_f32 v13, -v63, v3, v13
	v_fma_f32 v14, -v67, v3, v14
	v_fma_f32 v15, -v71, v3, v15
	v_fma_f32 v16, -v75, v3, v16
	v_fma_f32 v17, -v79, v3, v17
	v_fma_f32 v5, -v32, v4, v5
	v_fma_f32 v6, -v36, v4, v6
	v_fma_f32 v7, -v40, v4, v7
	v_fma_f32 v8, -v44, v4, v8
	v_fma_f32 v9, -v48, v4, v9
	v_fma_f32 v10, -v52, v4, v10
	v_fma_f32 v11, -v56, v4, v11
	v_fma_f32 v12, -v60, v4, v12
	v_fma_f32 v13, -v64, v4, v13
	v_fma_f32 v14, -v68, v4, v14
	v_fma_f32 v15, -v72, v4, v15
	v_fma_f32 v16, -v76, v4, v16
	v_fma_f32 v17, -v80, v4, v17
	v_fma_f32 v6, -v37, v5, v6
	v_fma_f32 v7, -v41, v5, v7
	v_fma_f32 v8, -v45, v5, v8
	v_fma_f32 v9, -v49, v5, v9
	v_fma_f32 v10, -v53, v5, v10
	v_fma_f32 v11, -v57, v5, v11
	v_fma_f32 v12, -v61, v5, v12
	v_fma_f32 v13, -v65, v5, v13
	v_fma_f32 v14, -v69, v5, v14
	v_fma_f32 v15, -v73, v5, v15
	v_fma_f32 v16, -v77, v5, v16
	v_fma_f32 v17, -v81, v5, v17
	s_waitcnt lgkmcnt(0)
	ds_read_b128 v[134:137], v241 offset:2480
	ds_read_b128 v[138:141], v241 offset:2752
	ds_read_b128 v[142:145], v241 offset:3024
	ds_read_b128 v[146:149], v241 offset:3296
	ds_read_b128 v[150:153], v241 offset:3568
	ds_read_b128 v[158:161], v241 offset:3840
	ds_read_b128 v[162:165], v241 offset:4112
	v_fma_f32 v7, -v82, v6, v7
	v_fma_f32 v8, -v86, v6, v8
	v_fma_f32 v9, -v90, v6, v9
	v_fma_f32 v10, -v96, v6, v10
	v_fma_f32 v11, -v100, v6, v11
	v_fma_f32 v12, -v110, v6, v12
	v_fma_f32 v13, -v114, v6, v13
	v_fma_f32 v14, -v118, v6, v14
	v_fma_f32 v15, -v122, v6, v15
	v_fma_f32 v16, -v126, v6, v16
	v_fma_f32 v17, -v130, v6, v17
	v_fma_f32 v8, -v87, v7, v8
	v_fma_f32 v9, -v91, v7, v9
	v_fma_f32 v10, -v97, v7, v10
	v_fma_f32 v11, -v101, v7, v11
	v_fma_f32 v12, -v111, v7, v12
	v_fma_f32 v13, -v115, v7, v13
	v_fma_f32 v14, -v119, v7, v14
	v_fma_f32 v15, -v123, v7, v15
	v_fma_f32 v16, -v127, v7, v16
	v_fma_f32 v17, -v131, v7, v17
	v_fma_f32 v9, -v92, v8, v9
	v_fma_f32 v10, -v98, v8, v10
	v_fma_f32 v11, -v102, v8, v11
	v_fma_f32 v12, -v112, v8, v12
	v_fma_f32 v13, -v116, v8, v13
	v_fma_f32 v14, -v120, v8, v14
	v_fma_f32 v15, -v124, v8, v15
	v_fma_f32 v16, -v128, v8, v16
	v_fma_f32 v17, -v132, v8, v17
	v_fma_f32 v10, -v99, v9, v10
	v_fma_f32 v11, -v103, v9, v11
	v_fma_f32 v12, -v113, v9, v12
	v_fma_f32 v13, -v117, v9, v13
	v_fma_f32 v14, -v121, v9, v14
	v_fma_f32 v15, -v125, v9, v15
	v_fma_f32 v16, -v129, v9, v16
	v_fma_f32 v17, -v133, v9, v17
	s_waitcnt lgkmcnt(0)
; __device__ __forceinline__ unsigned pack2(float lo, float hi) { return pg8::cvt_pk_bf16(lo, hi); }
; __device__ void prep_unit(unsigned char* lds, int bh, int n, const bf16_t* pc, const float* scal, const float* convw  , float alog, float dtb, unsigned char* unit, float* egl, unsigned* flag, unsigned fval) {
;     ...
;             bf16_t* sf = stage + (rb * 2 + (c >> 5)) * 512 + ((c >> 3) & 3) * 128 + (c & 7);
; #pragma unroll
;             for (int r = 0; r < 16; r += 2) {
;                 Am[(16 * rb + r) * 68 + c] = sx[r]; Am[(16 * rb + r + 1) * 68 + c] = sx[r + 1];
;                 const unsigned ph = pack2(sx[r], sx[r + 1]);
;                 const unsigned pl = pack2(sx[r] - __uint_as_float(ph << 16), sx[r + 1] - __uint_as_float(ph & 0xffff0000u));
;                 sf[r * 8] = (bf16_t)(ph & 0xffffu); sf[(r + 1) * 8] = (bf16_t)(ph >> 16);
;                 sf[4096 + r * 8] = (bf16_t)(pl & 0xffffu); sf[4096 + (r + 1) * 8] = (bf16_t)(pl >> 16);
;             }
;     ...
;         const int quad = lane >> 4, cl = lane & 15;
;         bf16x8 th[4][2], tl[4][2];
; #pragma unroll
;         for (int mt = 0; mt < 4; ++mt)
; #pragma unroll
;             for (int ks = 0; ks < 2; ++ks) { th[mt][ks] = *(const bf16x8*)((const unsigned char*)stage + ((mt * 2 + ks) * 512 + lane * 8) * 2); tl[mt][ks] = *(const bf16x8*)((const unsigned char*)stage + 8192 + ((mt * 2 + ks) * 512 + lane * 8) * 2); }
; #pragma unroll
;         for (int nt = 0; nt < 2; ++nt) {
;             const int col = 32 * wid + 16 * nt + cl; const float* src = col < 128 ? vT + col * 68 : kT + (col - 128) * 68;
;             bf16x8 bh_[2], bl_[2];
; #pragma unroll
;             for (int ks = 0; ks < 2; ++ks) { const int s0 = 32 * ks + quad * 8; float x[8];
;                 const f32x4 r0 = *(const f32x4*)(src + s0), r1 = *(const f32x4*)(src + s0 + 4), b0 = *(const f32x4*)(bet + s0), b1 = *(const f32x4*)(bet + s0 + 4);
; #pragma unroll
;                 for (int j = 0; j < 4; ++j) { x[j] = r0[j] * b0[j]; x[4 + j] = r1[j] * b1[j]; }
;                 if (col >= 128) {
; #pragma unroll
;                     for (int j = 0; j < 8; ++j) x[j] *= rk[s0 + j] * __expf(gc[s0 + j]); }
;                 split_bf16(x, bh_[ks], bl_[ks]); }
	ds_read_b128 v[166:169], v241 offset:3584
	ds_read_b128 v[182:185], v241 offset:3856
	ds_read_b128 v[186:189], v241 offset:4128
	v_fma_f32 v11, -v134, v10, v11
	v_fma_f32 v12, -v138, v10, v12
	v_fma_f32 v13, -v142, v10, v13
	v_fma_f32 v14, -v146, v10, v14
	v_fma_f32 v15, -v150, v10, v15
	v_fma_f32 v16, -v158, v10, v16
	v_fma_f32 v17, -v162, v10, v17
	v_fma_f32 v12, -v139, v11, v12
	v_fma_f32 v13, -v143, v11, v13
	v_fma_f32 v14, -v147, v11, v14
	v_fma_f32 v15, -v151, v11, v15
	v_fma_f32 v16, -v159, v11, v16
	v_fma_f32 v17, -v163, v11, v17
	v_fma_f32 v13, -v144, v12, v13
	v_fma_f32 v14, -v148, v12, v14
	v_fma_f32 v15, -v152, v12, v15
	v_fma_f32 v16, -v160, v12, v16
	v_fma_f32 v17, -v164, v12, v17
	v_fma_f32 v14, -v149, v13, v14
	v_fma_f32 v15, -v153, v13, v15
	v_fma_f32 v16, -v161, v13, v16
	v_fma_f32 v17, -v165, v13, v17
	s_waitcnt lgkmcnt(0)
	v_fma_f32 v15, -v166, v14, v15
	v_fma_f32 v16, -v182, v14, v16
	v_fma_f32 v17, -v186, v14, v17
	v_fma_f32 v16, -v183, v15, v16
	v_fma_f32 v17, -v187, v15, v17
	v_fma_f32 v17, -v188, v16, v17
	ds_write_b32 v240, v2 offset:13056
	ds_write_b32 v240, v3 offset:13328
	ds_write_b32 v240, v4 offset:13600
	ds_write_b32 v240, v5 offset:13872
	ds_write_b32 v240, v6 offset:14144
	ds_write_b32 v240, v7 offset:14416
	ds_write_b32 v240, v8 offset:14688
	ds_write_b32 v240, v9 offset:14960
	ds_write_b32 v240, v10 offset:15232
	ds_write_b32 v240, v11 offset:15504
	ds_write_b32 v240, v12 offset:15776
	ds_write_b32 v240, v13 offset:16048
	ds_write_b32 v240, v14 offset:16320
	ds_write_b32 v240, v15 offset:16592
	ds_write_b32 v240, v16 offset:16864
	ds_write_b32 v240, v17 offset:17136
	s_waitcnt lgkmcnt(0)
.LBB0_414:
	s_or_b64 exec, exec, s[0:1]
	v_lshlrev_b32_e32 v50, 4, v157
	v_readlane_b32 s0, v254, 7
	v_readlane_b32 s1, v254, 10
	s_waitcnt lgkmcnt(0)
	v_add_u32_e32 v2, s0, v50
	s_barrier
	v_lshrrev_b32_e32 v206, 3, v156
	v_and_b32_e32 v207, 7, v156
	v_mul_u32_u24_e32 v208, 0x110, v206
	v_lshl_add_u32 v208, v207, 5, v208
	v_add_u32_e32 v208, 0x19800, v208
	ds_read_b128 v[182:185], v208
	ds_read_b128 v[186:189], v208 offset:16
	v_lshrrev_b32_e32 v209, 4, v206
	v_bfe_u32 v210, v156, 2, 1
	v_lshl_add_u32 v209, v209, 1, v210
	v_and_b32_e32 v210, 3, v156
	v_lshlrev_b32_e32 v209, 10, v209
	v_lshl_add_u32 v209, v210, 8, v209
	v_and_b32_e32 v210, 15, v206
	v_lshl_add_u32 v209, v210, 4, v209
	v_add_u32_e32 v209, 0x22400, v209
	s_waitcnt lgkmcnt(0)
	v_cvt_pk_bf16_f32 v190, v182, v183
	v_cvt_pk_bf16_f32 v191, v184, v185
	v_cvt_pk_bf16_f32 v192, v186, v187
	v_cvt_pk_bf16_f32 v193, v188, v189
	v_lshlrev_b32_e32 v198, 16, v190
	v_and_b32_e32 v199, 0xffff0000, v190
	v_lshlrev_b32_e32 v200, 16, v191
	v_and_b32_e32 v201, 0xffff0000, v191
	v_lshlrev_b32_e32 v202, 16, v192
	v_and_b32_e32 v203, 0xffff0000, v192
	v_lshlrev_b32_e32 v204, 16, v193
	v_and_b32_e32 v205, 0xffff0000, v193
	v_sub_f32_e32 v198, v182, v198
	v_sub_f32_e32 v199, v183, v199
	v_sub_f32_e32 v200, v184, v200
	v_sub_f32_e32 v201, v185, v201
	v_sub_f32_e32 v202, v186, v202
	v_sub_f32_e32 v203, v187, v203
	v_sub_f32_e32 v204, v188, v204
	v_sub_f32_e32 v205, v189, v205
	v_cvt_pk_bf16_f32 v194, v198, v199
	v_cvt_pk_bf16_f32 v195, v200, v201
	v_cvt_pk_bf16_f32 v196, v202, v203
	v_cvt_pk_bf16_f32 v197, v204, v205
	ds_write_b128 v209, v[190:193]
	ds_write_b128 v209, v[194:197] offset:8192
	s_waitcnt lgkmcnt(0)
	s_barrier
	v_add_u32_e32 v3, s1, v50
	ds_read_b128 v[58:61], v2
	ds_read_b128 v[62:65], v3
	v_or_b32_e32 v2, 0x400, v50
	v_add_u32_e32 v3, s0, v2
	v_add_u32_e32 v6, s1, v2
	ds_read_b128 v[2:5], v3
	ds_read_b128 v[34:37], v6
	v_or_b32_e32 v6, 0x800, v50
	v_or_b32_e32 v14, 0xc00, v50
	v_or_b32_e32 v22, 0x1000, v50
	v_or_b32_e32 v30, 0x1400, v50
	v_or_b32_e32 v42, 0x1800, v50
	v_or_b32_e32 v50, 0x1c00, v50
	v_lshl_or_b32 v103, v106, 5, v108
	s_add_i32 s2, 0, 0x11000
	v_add_u32_e32 v7, s0, v6
	v_add_u32_e32 v15, s0, v14
	v_add_u32_e32 v23, s0, v22
	v_add_u32_e32 v31, s0, v30
	v_add_u32_e32 v43, s0, v42
	v_add_u32_e32 v51, s0, v50
	s_movk_i32 s0, 0x110
	v_mov_b32_e32 v67, s2
	v_cmp_gt_i32_e32 vcc, s46, v103
	v_mul_lo_u32 v66, v103, s0
	v_lshlrev_b32_e32 v68, 5, v107
	v_cndmask_b32_e32 v67, 0, v67, vcc
	v_add3_u32 v74, v67, v66, v68
	v_add_u32_e32 v66, 0, v68
	v_add_u32_e32 v10, s1, v6
	v_add_u32_e32 v18, s1, v14
	v_add_u32_e32 v26, s1, v22
	v_add_u32_e32 v38, s1, v30
	v_add_u32_e32 v46, s1, v42
	v_add_u32_e32 v54, s1, v50
	v_add_u32_e32 v70, 0x22100, v66
	ds_read_b128 v[6:9], v7
	ds_read_b128 v[10:13], v10
	ds_read_b128 v[14:17], v15
	ds_read_b128 v[18:21], v18
	ds_read_b128 v[22:25], v23
	ds_read_b128 v[26:29], v26
	ds_read_b128 v[30:33], v31
	ds_read_b128 v[38:41], v38
	ds_read_b128 v[42:45], v43
	ds_read_b128 v[46:49], v46
	ds_read_b128 v[50:53], v51
	ds_read_b128 v[54:57], v54
	ds_read_b128 v[82:85], v70
	ds_read_b128 v[66:69], v74
	ds_read_b128 v[86:89], v74 offset:16
	ds_read_b128 v[78:81], v70 offset:16
	v_lshlrev_b32_e32 v100, 3, v107
	s_movk_i32 s0, 0x7f
	v_cmp_lt_i32_e32 vcc, s0, v103
	s_waitcnt lgkmcnt(0)
	v_pk_mul_f32 v[70:71], v[68:69], v[84:85]
	v_pk_mul_f32 v[72:73], v[66:67], v[82:83]
	v_pk_mul_f32 v[66:67], v[88:89], v[80:81]
	v_pk_mul_f32 v[68:69], v[86:87], v[78:79]
	v_lshlrev_b32_e32 v101, 2, v100
	s_and_saveexec_b64 s[0:1], vcc
	s_cbranch_execz .LBB0_416
	s_add_i32 s3, 0, 0x22000
	v_add_u32_e32 v76, s3, v101
	ds_read_b128 v[86:89], v76
	v_readlane_b32 s4, v254, 8
	s_nop 1
	v_add_u32_e32 v75, s4, v101
	ds_read_b128 v[90:93], v75
	s_waitcnt lgkmcnt(0)
	v_mul_f32_e32 v76, 0x3fb8aa3b, v86
	v_mul_f32_e32 v77, 0x3fb8aa3b, v87
	v_exp_f32_e32 v76, v76
	v_exp_f32_e32 v77, v77
	v_mul_f32_e32 v75, 0x3fb8aa3b, v88
	v_pk_mul_f32 v[76:77], v[90:91], v[76:77]
	s_nop 0
	v_pk_mul_f32 v[72:73], v[72:73], v[76:77]
	v_exp_f32_e32 v76, v75
	v_mul_f32_e32 v75, 0x3fb8aa3b, v89
	v_exp_f32_e32 v77, v75
	v_or_b32_e32 v75, 16, v101
	v_add_u32_e32 v90, s4, v75
	v_add_u32_e32 v75, s3, v75
	ds_read_b128 v[86:89], v75
	v_pk_mul_f32 v[76:77], v[92:93], v[76:77]
	ds_read_b128 v[90:93], v90
	v_pk_mul_f32 v[70:71], v[70:71], v[76:77]
	s_waitcnt lgkmcnt(0)
	v_mul_f32_e32 v75, 0x3fb8aa3b, v86
	v_exp_f32_e32 v76, v75
	v_mul_f32_e32 v75, 0x3fb8aa3b, v87
	v_exp_f32_e32 v77, v75
	v_mul_f32_e32 v75, 0x3fb8aa3b, v88
	v_pk_mul_f32 v[76:77], v[90:91], v[76:77]
	s_nop 0
	v_pk_mul_f32 v[68:69], v[68:69], v[76:77]
	v_exp_f32_e32 v76, v75
	v_mul_f32_e32 v75, 0x3fb8aa3b, v89
	v_exp_f32_e32 v77, v75
	s_nop 0
	v_pk_mul_f32 v[76:77], v[92:93], v[76:77]
	s_nop 0
	v_pk_mul_f32 v[66:67], v[66:67], v[76:77]

; __device__ __forceinline__ int my_tid() { int t = (int)threadIdx.x; asm volatile("" : "+v"(t)); return t; }
; __device__ void scan_unit(unsigned char* lds, int bh, int half, unsigned char* prep, const float* egl, const unsigned* uflag  , unsigned fval) {
;     const int tid = my_tid(), lane = tid & 63, b = bh >> 2, h = bh & 3, quad = lane >> 4, cl = lane & 15;
;     const int wid = __builtin_amdgcn_readfirstlane(tid >> 6);
;     unsigned char* ubase = prep + (size_t)bh * 128 * PREP_UNIT;
;     int ready = 0;
;     (void)b; (void)h;
;     ...
;     if (wid >= 4) {
; __device__ void run_phase(const Params& p, unsigned char* lds, int ph) {
;     ...
;             else if (it < 48) { const int j = it - 16;
;                 for (int rep = 0; rep < REP_SCAN; ++rep) { scan_unit(lds, j >> 1, j & 1, ws + WS_PREP, (const float*)(ws + WS_EGL), uflag + (j >> 1) * 128, fval); __syncthreads(); } }
.LBB0_449:
	s_or_b64 exec, exec, s[12:13]
	s_branch .Lrp_0
	s_nop 0
	s_nop 0
	s_nop 0
	s_nop 0
	s_nop 0
	s_nop 0
	s_nop 0
	s_nop 0
	s_nop 0
	s_nop 0
	s_nop 0
	s_nop 0
	s_nop 0
	s_nop 0
	s_nop 0
	s_nop 0
	s_nop 0
	s_nop 0
	s_nop 0
	s_nop 0
	s_nop 0
	s_nop 0
	s_nop 0
	s_nop 0
	s_nop 0
	s_nop 0
	s_nop 0
	s_nop 0
	s_nop 0
	s_nop 0
	s_nop 0
	s_nop 0
	s_nop 0
	s_nop 0
	s_nop 0
	s_nop 0
	s_nop 0
	s_nop 0
	s_nop 0
	s_nop 0
	s_nop 0
	s_nop 0
	s_nop 0
	s_nop 0
	s_nop 0
	s_nop 0
	s_nop 0
	s_nop 0
	s_nop 0
	s_nop 0
	s_nop 0
	s_nop 0
	s_nop 0
	s_nop 0
	s_nop 0
	s_nop 0
	s_nop 0
	s_nop 0
	s_nop 0
	s_nop 0
	s_nop 0
	s_nop 0
	s_nop 0
	s_nop 0
	s_nop 0
	s_nop 0
	s_nop 0
	s_nop 0
	s_nop 0
	s_nop 0
	s_nop 0
	s_nop 0
	s_nop 0
	s_nop 0
	s_nop 0
	s_nop 0
	s_nop 0
	s_nop 0
	s_nop 0
	s_nop 0
	s_nop 0
	s_nop 0
	s_nop 0
	s_nop 0
	s_nop 0
	s_nop 0
	s_nop 0
	s_nop 0
	s_nop 0
	s_nop 0
	s_nop 0
	s_nop 0
	s_nop 0
	s_nop 0
	s_nop 0
	s_nop 0
	s_nop 0
	s_nop 0
	s_nop 0
	s_nop 0
	s_nop 0
.Lrp_0:
.LBB0_450:
	s_or_saveexec_b64 s[0:1], s[4:5]
	s_mov_b64 s[4:5], s[56:57]
	s_xor_b64 exec, exec, s[0:1]
	s_cbranch_execz .LBB0_619
	v_add_u32_e32 v0, -16, v90
	v_lshrrev_b32_e32 v0, 1, v0
	v_readlane_b32 s2, v255, 11
	s_waitcnt vmcnt(0)
	v_lshlrev_b32_e32 v52, 7, v0
	v_mov_b32_e32 v53, v1
	v_readlane_b32 s3, v255, 12
	v_mov_b32_e32 v50, v212
	s_nop 0
	v_lshl_add_u64 v[178:179], v[52:53], 2, s[2:3]
	s_mov_b32 s2, 0x900000
	v_mul_lo_u32 v0, v0, s2
	v_readlane_b32 s2, v255, 39
	v_readlane_b32 s3, v255, 40
	s_nop 1
	v_lshl_add_u64 v[180:181], s[2:3], 0, v[0:1]
	v_readfirstlane_b32 s2, v50
	s_ashr_i32 s8, s2, 6
	s_cmp_lt_i32 s8, 4
	s_mov_b64 s[2:3], -1
	s_cbranch_scc0 .LBB0_533
	s_mov_b64 s[2:3], exec
	v_readlane_b32 s4, v254, 13
	v_readlane_b32 s5, v254, 14
	s_and_b64 s[4:5], s[2:3], s[4:5]
	s_mov_b64 exec, s[4:5]
	s_cbranch_execz .LBB0_461
	s_mov_b32 s9, 0
	s_branch .LBB0_456
